# v151 with sc1 added to the nt x loads of phase 0
# speedup vs baseline: 1.0018x; 1.0018x over previous
.LBB0_25:
	v_add_u32_e32 v2, 0xffffc000, v0
	v_lshlrev_b64 v[24:25], 12, v[2:3]
	v_lshl_add_u64 v[24:25], s[10:11], 0, v[24:25]
	v_cmp_gt_i32_e64 s[6:7], s5, v0
	v_mov_b32_e32 v11, v3
	s_nop 0
	v_cndmask_b32_e64 v25, v25, v7, s[6:7]
	v_cndmask_b32_e64 v24, v24, v6, s[6:7]
	v_lshl_add_u64 v[36:37], v[24:25], 0, v[10:11]
	global_load_dwordx4 v[24:27], v[36:37], off sc1 nt
	global_load_dwordx4 v[28:31], v[36:37], off offset:1024 sc1 nt
	global_load_dwordx4 v[32:35], v[36:37], off offset:2048 sc1 nt
	global_load_dwordx4 v[36:39], v[36:37], off offset:3072 sc1 nt
	v_cmp_lt_i32_e64 s[6:7], v16, v17
	s_waitcnt vmcnt(3)
	v_cvt_pk_bf16_f32 v40, v24, v25
	v_cvt_pk_bf16_f32 v41, v26, v27
	global_store_dwordx2 v[12:13], v[40:41], off
	v_mul_f32_e32 v11, v25, v25
	v_fmac_f32_e32 v11, v24, v24
	v_fmac_f32_e32 v11, v26, v26
	v_fmac_f32_e32 v11, v27, v27
	v_cndmask_b32_e64 v2, v15, v16, s[6:7]
	v_lshlrev_b32_e32 v2, 2, v2
	v_cmp_lt_i32_e64 s[6:7], v18, v17
	s_waitcnt vmcnt(3)
	v_cvt_pk_bf16_f32 v42, v28, v29
	v_cvt_pk_bf16_f32 v43, v30, v31
	global_store_dwordx2 v[12:13], v[42:43], off offset:512
	s_waitcnt lgkmcnt(0)
	v_mul_f32_e32 v23, v29, v29
	v_fmac_f32_e32 v23, v28, v28
	v_fmac_f32_e32 v23, v30, v30
	v_fmac_f32_e32 v23, v31, v31
	v_add_f32_e32 v11, v11, v23
	s_waitcnt vmcnt(3)
	v_cvt_pk_bf16_f32 v44, v32, v33
	v_cvt_pk_bf16_f32 v45, v34, v35
	global_store_dwordx2 v[12:13], v[44:45], off offset:1024
	v_mul_f32_e32 v23, v33, v33
	v_fmac_f32_e32 v23, v32, v32
	v_fmac_f32_e32 v23, v34, v34
	v_fmac_f32_e32 v23, v35, v35
	v_add_f32_e32 v11, v11, v23
	s_waitcnt vmcnt(3)
	v_mul_f32_e32 v23, v37, v37
	v_fmac_f32_e32 v23, v36, v36
	v_fmac_f32_e32 v23, v38, v38
	v_fmac_f32_e32 v23, v39, v39
	v_add_f32_e32 v11, v11, v23
	v_cvt_pk_bf16_f32 v24, v36, v37
	v_cvt_pk_bf16_f32 v25, v38, v39
	global_store_dwordx2 v[12:13], v[24:25], off offset:1536
	s_mov_b64 s[6:7], s[24:25]
	s_nop 1
	v_add_f32_dpp v11, v11, v11 quad_perm:[1,0,3,2] row_mask:0xf bank_mask:0xf bound_ctrl:1
	s_nop 1
	v_add_f32_dpp v11, v11, v11 quad_perm:[2,3,0,1] row_mask:0xf bank_mask:0xf bound_ctrl:1
	s_nop 1
	v_add_f32_dpp v11, v11, v11 row_half_mirror row_mask:0xf bank_mask:0xf bound_ctrl:1
	s_nop 1
	v_add_f32_dpp v11, v11, v11 row_mirror row_mask:0xf bank_mask:0xf bound_ctrl:1
	v_mov_b32_e32 v23, v11
	s_nop 1
	v_permlane16_swap_b32_e32 v11, v23
	s_nop 0
	v_add_f32_e32 v11, v11, v23
	v_mov_b32_e32 v23, v11
	s_nop 1
	v_permlane32_swap_b32_e32 v11, v23
	s_nop 0
	v_add_f32_e32 v11, v11, v23
	v_mov_b32_e32 v23, 0
	s_and_saveexec_b64 s[28:29], vcc
	s_cbranch_execz .LBB0_27
	s_waitcnt lgkmcnt(0)
	v_add_f32_e32 v2, v11, v23
	v_fmamk_f32 v2, v2, 0x3a800000, v1
	v_mul_f32_e32 v11, 0x4b800000, v2
	v_cmp_gt_f32_e64 s[6:7], s17, v2
	s_nop 1
	v_cndmask_b32_e64 v2, v2, v11, s[6:7]
	v_rsq_f32_e32 v2, v2
	s_nop 0
	v_mul_f32_e32 v11, 0x45800000, v2
	v_cndmask_b32_e64 v2, v2, v11, s[6:7]
	s_or_b64 s[6:7], s[24:25], exec
